# v24 plus NA V fragments loaded as 16-byte pieces (4 loads instead of 8 per key block) with a permlane32 exchange in front of the PV MFMAs
# speedup vs baseline: 1.0226x; 1.0085x over previous
.LBB0_246:
	s_or_b64 exec, exec, s[0:1]
	v_lshrrev_b32_e32 v0, 3, v69
	v_and_b32_e32 v1, 4, v69
	v_and_or_b32 v0, v0, 56, v1
	v_lshrrev_b32_e32 v0, 1, v0
	v_or_b32_e32 v77, v0, v92
	v_lshlrev_b32_e32 v1, 4, v69
	v_sub_u32_e64 v2, v0, 4 clamp
	v_sub_u32_e64 v0, v0, 3 clamp
	v_and_b32_e32 v36, 48, v1
	v_ashrrev_i32_e32 v35, 9, v69
	v_min_u32_e32 v96, 24, v2
	v_min_u32_e32 v0, 24, v0
	v_or_b32_e32 v32, v36, v93
	v_lshlrev_b32_e32 v1, 6, v77
	v_lshlrev_b32_e32 v34, 11, v35
	v_sub_u32_e32 v0, v0, v96
	v_or3_b32 v80, v1, v34, v32
	v_lshlrev_b32_e32 v1, 6, v33
	v_add_u32_e32 v97, 8, v0
	v_mov_b32_e32 v15, 0
	v_ashrrev_i32_e32 v81, 31, v80
	v_cmp_lt_i32_e32 vcc, 0, v97
	v_lshlrev_b32_e32 v82, 1, v1
	v_mov_b32_e32 v14, v15
	v_mov_b32_e32 v13, v15
	v_mov_b32_e32 v12, v15
	v_mov_b32_e32 v11, v15
	v_mov_b32_e32 v10, v15
	v_mov_b32_e32 v9, v15
	v_mov_b32_e32 v8, v15
	v_mov_b32_e32 v7, v15
	v_mov_b32_e32 v6, v15
	v_mov_b32_e32 v5, v15
	v_mov_b32_e32 v4, v15
	v_mov_b32_e32 v3, v15
	v_mov_b32_e32 v2, v15
	v_mov_b32_e32 v1, v15
	v_mov_b32_e32 v0, v15
	v_mov_b32_e32 v31, v15
	v_mov_b32_e32 v30, v15
	v_mov_b32_e32 v29, v15
	v_mov_b32_e32 v28, v15
	v_mov_b32_e32 v27, v15
	v_mov_b32_e32 v26, v15
	v_mov_b32_e32 v25, v15
	v_mov_b32_e32 v24, v15
	v_mov_b32_e32 v23, v15
	v_mov_b32_e32 v22, v15
	v_mov_b32_e32 v21, v15
	v_mov_b32_e32 v20, v15
	v_mov_b32_e32 v19, v15
	v_mov_b32_e32 v18, v15
	v_mov_b32_e32 v17, v15
	v_mov_b32_e32 v16, v15
	v_mov_b32_e32 v117, v15
	s_waitcnt lgkmcnt(0)
	s_and_saveexec_b64 s[2:3], vcc
	s_cbranch_execz .LBB0_243
	v_writelane_b32 v254, s2, 57
	v_max_i32_e32 v0, 4, v77
	v_add_u32_e32 v3, -4, v0
	v_writelane_b32 v254, s3, 58
	v_writelane_b32 v254, s16, 59
	v_mov_b32_e32 v83, v65
	v_mov_b32_e32 v75, v65
	v_writelane_b32 v254, s17, 60
	v_sub_u32_e64 v2, v36, 8 clamp
	v_readlane_b32 s0, v254, 49
	v_readlane_b32 s1, v254, 50
	v_min_u32_e32 v98, 24, v3
	v_mov_b32_e32 v117, 0
	v_mov_b64_e32 v[0:1], s[0:1]
	v_mad_i64_i32 v[0:1], s[0:1], v80, s89, v[0:1]
	v_lshl_add_u64 v[0:1], v[0:1], 0, v[82:83]
	v_lshl_add_u64 v[0:1], v[0:1], 0, v[74:75]
	global_load_dwordx4 v[48:51], v[0:1], off
	global_load_dwordx4 v[52:55], v[0:1], off offset:32
	global_load_dwordx4 v[56:59], v[0:1], off offset:64
	global_load_dwordx4 v[60:63], v[0:1], off offset:96
	v_min_u32_e32 v75, 32, v2
	v_or_b32_e32 v4, v75, v68
	v_max_i32_e32 v2, 8, v32
	v_sub_u32_e32 v5, v4, v32
	v_add_u32_e32 v161, 15, v5
	v_add_u32_e32 v2, -8, v2
	v_max_i32_e32 v5, -15, v5
	v_min_u32_e32 v2, 48, v2
	v_add_u32_e32 v5, 15, v5
	v_add_u32_e32 v3, 16, v2
	v_min_u32_e32 v101, 30, v5
	v_or_b32_e32 v5, 1, v4
	v_cmp_ge_u32_e64 s[6:7], v5, v2
	v_cmp_lt_u32_e64 s[8:9], v5, v3
	v_sub_u32_e32 v5, v5, v32
	v_max_i32_e32 v5, -15, v5
	v_add_u32_e32 v5, 15, v5
	v_min_u32_e32 v102, 30, v5
	v_or_b32_e32 v5, 2, v4
	v_cmp_ge_u32_e64 s[10:11], v5, v2
	v_cmp_lt_u32_e64 s[12:13], v5, v3
	v_sub_u32_e32 v5, v5, v32
	v_max_i32_e32 v5, -15, v5
	v_add_u32_e32 v5, 15, v5
	v_min_u32_e32 v103, 30, v5
	v_or_b32_e32 v5, 3, v4
	v_cmp_ge_u32_e64 s[14:15], v5, v2
	v_cmp_lt_u32_e64 s[16:17], v5, v3
	v_sub_u32_e32 v5, v5, v32
	v_max_i32_e32 v5, -15, v5
	v_add_u32_e32 v5, 15, v5
	v_min_u32_e32 v104, 30, v5
	v_add_u32_e32 v5, 8, v4
	v_cmp_ge_u32_e64 s[18:19], v5, v2
	v_cmp_lt_u32_e64 s[20:21], v5, v3
	v_sub_u32_e32 v5, v5, v32
	v_max_i32_e32 v5, -15, v5
	v_add_u32_e32 v5, 15, v5
	v_min_u32_e32 v105, 30, v5
	v_add_u32_e32 v5, 9, v4
	v_cmp_ge_u32_e64 s[22:23], v5, v2
	v_cmp_lt_u32_e64 s[24:25], v5, v3
	v_sub_u32_e32 v5, v5, v32
	v_max_i32_e32 v5, -15, v5
	v_add_u32_e32 v5, 15, v5
	v_min_u32_e32 v106, 30, v5
	v_add_u32_e32 v5, 10, v4
	v_cmp_ge_u32_e64 s[26:27], v5, v2
	v_cmp_lt_u32_e64 s[28:29], v5, v3
	v_sub_u32_e32 v5, v5, v32
	v_max_i32_e32 v5, -15, v5
	v_add_u32_e32 v5, 15, v5
	v_min_u32_e32 v107, 30, v5
	v_add_u32_e32 v5, 11, v4
	v_cmp_ge_u32_e64 s[30:31], v5, v2
	v_cmp_lt_u32_e64 s[34:35], v5, v3
	v_sub_u32_e32 v5, v5, v32
	v_max_i32_e32 v5, -15, v5
	v_add_u32_e32 v5, 15, v5
	v_min_u32_e32 v108, 30, v5
	v_add_u32_e32 v5, 16, v4
	v_cmp_ge_u32_e64 s[36:37], v5, v2
	v_sub_u32_e32 v5, v5, v32
	v_max_i32_e32 v5, -15, v5
	v_add_u32_e32 v5, 15, v5
	v_min_u32_e32 v109, 30, v5
	v_add_u32_e32 v5, 17, v4
	v_cmp_ge_u32_e64 s[40:41], v5, v2
	v_cmp_lt_u32_e64 s[42:43], v5, v3
	v_sub_u32_e32 v5, v5, v32
	v_max_i32_e32 v5, -15, v5
	v_add_u32_e32 v5, 15, v5
	v_min_u32_e32 v110, 30, v5
	v_add_u32_e32 v5, 18, v4
	v_cmp_ge_u32_e64 s[44:45], v5, v2
	v_cmp_lt_u32_e64 s[46:47], v5, v3
	v_sub_u32_e32 v5, v5, v32
	v_max_i32_e32 v5, -15, v5
	v_add_u32_e32 v5, 15, v5
	v_min_u32_e32 v111, 30, v5
	v_add_u32_e32 v5, 19, v4
	v_cmp_ge_u32_e64 s[48:49], v5, v2
	v_cmp_lt_u32_e64 s[50:51], v5, v3
	v_sub_u32_e32 v5, v5, v32
	v_max_i32_e32 v5, -15, v5
	v_add_u32_e32 v5, 15, v5
	v_min_u32_e32 v112, 30, v5
	v_add_u32_e32 v5, 24, v4
	v_cmp_ge_u32_e64 s[52:53], v5, v2
	v_cmp_lt_u32_e64 s[54:55], v5, v3
	v_sub_u32_e32 v5, v5, v32
	v_max_i32_e32 v5, -15, v5
	v_add_u32_e32 v5, 15, v5
	v_mad_i32_i24 v0, v35, 10, v33
	v_min_u32_e32 v113, 30, v5
	v_add_u32_e32 v5, 25, v4
	v_ashrrev_i32_e32 v1, 31, v0
	v_cmp_ge_u32_e64 s[56:57], v5, v2
	v_cmp_lt_u32_e64 s[58:59], v5, v3
	v_sub_u32_e32 v5, v5, v32
	v_lshlrev_b64 v[0:1], 18, v[0:1]
	v_max_i32_e32 v5, -15, v5
	v_lshl_add_u64 v[0:1], v[66:67], 0, v[0:1]
	s_mov_b64 s[0:1], 0x20000
	v_add_u32_e32 v5, 15, v5
	v_lshl_add_u64 v[84:85], v[0:1], 0, s[0:1]
	v_cmp_ge_u32_e64 s[0:1], v4, v2
	v_cmp_lt_u32_e64 s[4:5], v4, v3
	v_cmp_lt_u32_e64 s[38:39], v4, v2
	v_min_u32_e32 v114, 30, v5
	v_add_u32_e32 v5, 26, v4
	v_add_u32_e32 v4, 27, v4
	v_cmp_ge_u32_e64 s[60:61], v5, v2
	v_cmp_lt_u32_e64 s[62:63], v5, v3
	v_sub_u32_e32 v5, v5, v32
	v_cmp_ge_u32_e64 s[64:65], v4, v2
	v_sub_u32_e32 v2, v4, v32
	v_max_i32_e32 v5, -15, v5
	v_max_i32_e32 v2, -15, v2
	v_writelane_b32 v254, s0, 61
	v_add_u32_e32 v5, 15, v5
	v_add_u32_e32 v2, 15, v2
	v_or_b32_e32 v99, v34, v90
	v_add_u32_e32 v100, 8, v98
	v_writelane_b32 v254, s1, 62
	v_min_u32_e32 v115, 30, v5
	v_cmp_lt_u32_e64 s[66:67], v4, v3
	v_min_u32_e32 v116, 30, v2
	v_lshl_add_u64 v[86:87], v[72:73], 0, v[82:83]
	v_lshl_add_u64 v[88:89], v[0:1], 0, v[78:79]
	s_mov_b32 s33, 0
	v_mov_b32_e32 v83, 0xf149f2ca
	s_mov_b64 s[0:1], 0
	v_mov_b32_e32 v0, 0
	v_mov_b32_e32 v1, v117
	v_mov_b32_e32 v2, v117
	v_mov_b32_e32 v3, v117
	v_mov_b32_e32 v4, v117
	v_mov_b32_e32 v5, v117
	v_mov_b32_e32 v6, v117
	v_mov_b32_e32 v7, v117
	v_mov_b32_e32 v8, v117
	v_mov_b32_e32 v9, v117
	v_mov_b32_e32 v10, v117
	v_mov_b32_e32 v11, v117
	v_mov_b32_e32 v12, v117
	v_mov_b32_e32 v13, v117
	v_mov_b32_e32 v14, v117
	v_mov_b32_e32 v15, v117
	v_mov_b32_e32 v16, 0
	v_mov_b32_e32 v17, v117
	v_mov_b32_e32 v18, v117
	v_mov_b32_e32 v19, v117
	v_mov_b32_e32 v20, v117
	v_mov_b32_e32 v21, v117
	v_mov_b32_e32 v22, v117
	v_mov_b32_e32 v23, v117
	v_mov_b32_e32 v24, v117
	v_mov_b32_e32 v25, v117
	v_mov_b32_e32 v26, v117
	v_mov_b32_e32 v27, v117
	v_mov_b32_e32 v28, v117
	v_mov_b32_e32 v29, v117
	v_mov_b32_e32 v30, v117
	v_mov_b32_e32 v31, v117
	v_lshrrev_b32_e32 v164, 5, v179
	v_lshlrev_b32_e32 v164, 3, v164
	v_mov_b32_e32 v165, 0
.LBB0_248:
	v_add_u32_e32 v32, s33, v96
	v_lshl_or_b32 v64, v32, 6, v75
	v_sub_u32_e32 v33, v32, v77
	v_cmp_ge_u32_e32 vcc, v32, v98
	v_cmp_lt_u32_e64 s[68:69], v32, v100
	v_add_u32_e32 v32, v99, v64
	v_max_i32_e32 v33, -7, v33
	v_mad_i64_i32 v[36:37], s[2:3], v32, s89, v[86:87]
	v_add_u32_e32 v38, 7, v33
	global_load_dwordx4 v[32:35], v[36:37], off offset:1024
	global_load_dwordx4 v[118:121], v[36:37], off offset:1056
	global_load_dwordx4 v[122:125], v[36:37], off offset:1088
	global_load_dwordx4 v[126:129], v[36:37], off offset:1120
	s_and_b64 s[84:85], vcc, s[68:69]
	v_min_u32_e32 v36, 14, v38
	s_movk_i32 vcc_lo, 0x7c
	v_mad_u32_u24 v130, v36, vcc_lo, v91
	v_lshl_add_u32 v160, v161, 2, v130
	ds_read_b32 v131, v160
	ds_read_b32 v132, v160 offset:4
	v_readlane_b32 s2, v254, 61
	v_readlane_b32 s3, v254, 62
	s_and_b64 s[2:3], s[84:85], s[2:3]
	s_and_b64 s[96:97], s[84:85], s[6:7]
	s_and_b64 s[94:95], s[84:85], s[10:11]
	s_and_b64 s[92:93], s[84:85], s[14:15]
	s_and_b64 s[96:97], s[96:97], s[8:9]
	s_and_b64 s[2:3], s[2:3], s[4:5]
	s_and_b64 s[90:91], s[84:85], s[18:19]
	s_and_b64 s[88:89], s[84:85], s[22:23]
	s_and_b64 s[94:95], s[94:95], s[12:13]
	s_and_b64 s[92:93], s[92:93], s[16:17]
	s_and_b64 s[86:87], s[84:85], s[26:27]
	s_and_b64 s[68:69], s[84:85], s[30:31]
	s_and_b64 s[90:91], s[90:91], s[20:21]
	s_and_b64 s[88:89], s[88:89], s[24:25]
	s_and_b64 s[70:71], s[84:85], s[36:37]
	s_and_b64 s[72:73], s[84:85], s[40:41]
	s_and_b64 s[86:87], s[86:87], s[28:29]
	s_and_b64 s[68:69], s[68:69], s[34:35]
	s_and_b64 s[74:75], s[84:85], s[44:45]
	s_and_b64 s[76:77], s[84:85], s[48:49]
	s_and_b64 s[70:71], s[70:71], s[38:39]
	s_and_b64 s[72:73], s[72:73], s[42:43]
	s_and_b64 s[78:79], s[84:85], s[52:53]
	s_and_b64 s[80:81], s[84:85], s[56:57]
	s_and_b64 s[74:75], s[74:75], s[46:47]
	s_and_b64 s[76:77], s[76:77], s[50:51]
	s_and_b64 s[82:83], s[84:85], s[60:61]
	s_and_b64 s[84:85], s[84:85], s[64:65]
	s_and_b64 s[78:79], s[78:79], s[54:55]
	s_and_b64 s[80:81], s[80:81], s[58:59]
	s_and_b64 s[82:83], s[82:83], s[62:63]
	s_and_b64 s[84:85], s[84:85], s[66:67]
	s_add_i32 s33, s33, 1
	v_cmp_ge_i32_e32 vcc, s33, v97
	s_or_b64 s[0:1], vcc, s[0:1]
	s_waitcnt vmcnt(3)
	v_mfma_f32_32x32x16_bf16 v[32:47], v[32:35], v[48:51], 0
	s_waitcnt vmcnt(2)
	v_mfma_f32_32x32x16_bf16 v[32:47], v[118:121], v[52:55], v[32:47]
	ds_read_b32 v118, v160 offset:8
	ds_read_b32 v119, v160 offset:12
	ds_read_b32 v120, v160 offset:32
	ds_read_b32 v121, v160 offset:36
	ds_read_b32 v133, v160 offset:40
	ds_read_b32 v134, v160 offset:44
	ds_read_b32 v135, v160 offset:64
	s_waitcnt vmcnt(1)
	v_mfma_f32_32x32x16_bf16 v[32:47], v[122:125], v[56:59], v[32:47]
	ds_read_b32 v122, v160 offset:68
	ds_read_b32 v123, v160 offset:72
	ds_read_b32 v124, v160 offset:76
	ds_read_b32 v125, v160 offset:96
	ds_read_b32 v136, v160 offset:100
	ds_read_b32 v137, v160 offset:104
	ds_read_b32 v130, v160 offset:108
	s_waitcnt vmcnt(0)
	v_mfma_f32_32x32x16_bf16 v[32:47], v[126:129], v[60:63], v[32:47]
	s_waitcnt lgkmcnt(14)
	s_nop 10
	v_add_f32_e32 v32, v32, v131
	v_add_f32_e32 v33, v33, v132
	s_waitcnt lgkmcnt(13)
	v_add_f32_e32 v34, v34, v118
	s_waitcnt lgkmcnt(12)
	v_add_f32_e32 v118, v35, v119
	v_max_f32_e32 v35, 0xf149f2ca, v32
	s_waitcnt lgkmcnt(11)
	v_add_f32_e32 v119, v36, v120
	v_cndmask_b32_e64 v36, v95, v33, s[96:97]
	v_cndmask_b32_e64 v35, v95, v35, s[2:3]
	s_waitcnt lgkmcnt(10)
	v_add_f32_e32 v120, v37, v121
	s_waitcnt lgkmcnt(9)
	v_add_f32_e32 v121, v38, v133
	v_cndmask_b32_e64 v37, v95, v34, s[94:95]
	v_cndmask_b32_e64 v38, v95, v118, s[92:93]
	v_max_f32_e32 v35, v35, v36
	s_waitcnt lgkmcnt(8)
	v_add_f32_e32 v126, v39, v134
	s_waitcnt lgkmcnt(7)
	v_add_f32_e32 v127, v40, v135
	v_cndmask_b32_e64 v39, v95, v119, s[90:91]
	v_cndmask_b32_e64 v40, v95, v120, s[88:89]
	v_max3_f32 v35, v35, v37, v38
	s_waitcnt lgkmcnt(6)
	v_add_f32_e32 v122, v41, v122
	s_waitcnt lgkmcnt(5)
	v_add_f32_e32 v123, v42, v123
	v_cndmask_b32_e64 v41, v95, v121, s[86:87]
	v_cndmask_b32_e64 v42, v95, v126, s[68:69]
	v_max3_f32 v35, v35, v39, v40
	s_waitcnt lgkmcnt(4)
	v_add_f32_e32 v124, v43, v124
	s_waitcnt lgkmcnt(3)
	v_add_f32_e32 v125, v44, v125
	v_cndmask_b32_e64 v43, v95, v127, s[70:71]
	v_cndmask_b32_e64 v44, v95, v122, s[72:73]
	v_max3_f32 v35, v35, v41, v42
	s_waitcnt lgkmcnt(2)
	v_add_f32_e32 v128, v45, v136
	s_waitcnt lgkmcnt(1)
	v_add_f32_e32 v129, v46, v137
	v_cndmask_b32_e64 v45, v95, v123, s[74:75]
	v_cndmask_b32_e64 v46, v95, v124, s[76:77]
	v_max3_f32 v35, v35, v43, v44
	s_waitcnt lgkmcnt(0)
	v_add_f32_e32 v130, v47, v130
	v_cndmask_b32_e64 v47, v95, v125, s[78:79]
	v_cndmask_b32_e64 v131, v95, v128, s[80:81]
	v_max3_f32 v35, v35, v45, v46
	v_cndmask_b32_e64 v132, v95, v129, s[82:83]
	v_cndmask_b32_e64 v133, v95, v130, s[84:85]
	v_max3_f32 v35, v35, v47, v131
	v_max3_f32 v35, v35, v132, v133
	v_mov_b32_e32 v36, v35
	s_nop 1
	v_permlane32_swap_b32_e32 v35, v36
	v_max3_f32 v131, v83, v35, v36
	v_sub_f32_e32 v32, v32, v131
	v_mul_f32_e32 v32, 0x3fb8aa3b, v32
	v_exp_f32_e32 v32, v32
	v_mov_b32_e32 v135, v117
	v_sub_f32_e32 v117, v118, v131
	v_sub_f32_e32 v118, v119, v131
	v_cndmask_b32_e64 v132, 0, v32, s[2:3]
	v_sub_f32_e32 v32, v33, v131
	v_mul_f32_e32 v32, 0x3fb8aa3b, v32
	v_exp_f32_e32 v32, v32
	v_sub_f32_e32 v119, v120, v131
	v_sub_f32_e32 v120, v121, v131
	v_sub_f32_e32 v121, v126, v131
	v_cndmask_b32_e64 v133, 0, v32, s[96:97]
	v_sub_f32_e32 v32, v34, v131
	v_mul_f32_e32 v32, 0x3fb8aa3b, v32
	v_exp_f32_e32 v32, v32
	v_mul_f32_e32 v117, 0x3fb8aa3b, v117
	v_mul_f32_e32 v118, 0x3fb8aa3b, v118
	v_mul_f32_e32 v119, 0x3fb8aa3b, v119
	v_cndmask_b32_e64 v134, 0, v32, s[94:95]
	v_lshlrev_b64 v[32:33], 1, v[64:65]
	v_lshl_add_u64 v[38:39], v[88:89], 0, v[32:33]
	v_lshl_add_u64 v[38:39], v[38:39], 0, v[164:165]
	v_lshl_add_u64 v[36:37], v[84:85], 0, v[32:33]
	global_load_dwordx4 v[32:35], v[38:39], off
	v_lshl_add_u64 v[46:47], v[36:37], 0, v[78:79]
	v_lshl_add_u64 v[46:47], v[46:47], 0, v[164:165]
	global_load_dwordx4 v[36:39], v[38:39], off offset:32
	s_nop 0
	s_nop 0
	global_load_dwordx4 v[40:43], v[46:47], off
	global_load_dwordx4 v[44:47], v[46:47], off offset:32
	s_nop 0
	v_sub_f32_e32 v64, v83, v131
	v_mul_f32_e32 v120, 0x3fb8aa3b, v120
	v_mul_f32_e32 v121, 0x3fb8aa3b, v121
	v_mul_f32_e32 v64, 0x3fb8aa3b, v64
	v_exp_f32_e32 v117, v117
	v_exp_f32_e32 v118, v118
	v_exp_f32_e32 v119, v119
	v_exp_f32_e32 v120, v120
	v_exp_f32_e32 v121, v121
	v_exp_f32_e32 v64, v64
	v_sub_f32_e32 v126, v127, v131
	v_sub_f32_e32 v122, v122, v131
	v_sub_f32_e32 v123, v123, v131
	v_sub_f32_e32 v124, v124, v131
	v_sub_f32_e32 v125, v125, v131
	v_sub_f32_e32 v127, v128, v131
	v_sub_f32_e32 v128, v129, v131
	v_sub_f32_e32 v129, v130, v131
	v_mov_b32_e32 v83, v131
	v_cndmask_b32_e64 v117, 0, v117, s[92:93]
	v_cndmask_b32_e64 v130, 0, v118, s[90:91]
	v_cndmask_b32_e64 v131, 0, v119, s[88:89]
	v_cndmask_b32_e64 v136, 0, v120, s[86:87]
	v_cndmask_b32_e64 v137, 0, v121, s[68:69]
	v_pk_mul_f32 v[14:15], v[14:15], v[64:65] op_sel_hi:[1,0]
	v_pk_mul_f32 v[12:13], v[12:13], v[64:65] op_sel_hi:[1,0]
	v_pk_mul_f32 v[10:11], v[10:11], v[64:65] op_sel_hi:[1,0]
	v_pk_mul_f32 v[8:9], v[8:9], v[64:65] op_sel_hi:[1,0]
	v_pk_mul_f32 v[6:7], v[6:7], v[64:65] op_sel_hi:[1,0]
	v_pk_mul_f32 v[4:5], v[4:5], v[64:65] op_sel_hi:[1,0]
	v_pk_mul_f32 v[2:3], v[2:3], v[64:65] op_sel_hi:[1,0]
	v_pk_mul_f32 v[0:1], v[0:1], v[64:65] op_sel_hi:[1,0]
	v_cvt_pk_bf16_f32 v118, v132, v133
	v_cvt_pk_bf16_f32 v119, v134, v117
	v_cvt_pk_bf16_f32 v120, v130, v131
	v_cvt_pk_bf16_f32 v121, v136, v137
	v_mul_f32_e32 v126, 0x3fb8aa3b, v126
	v_mul_f32_e32 v122, 0x3fb8aa3b, v122
	s_waitcnt vmcnt(3)
	v_permlane32_swap_b32_e32 v32, v34
	v_permlane32_swap_b32_e32 v33, v35
	s_nop 1
	v_mfma_f32_32x32x16_bf16 v[0:15], v[32:35], v[118:121], v[0:15]
	v_mul_f32_e32 v123, 0x3fb8aa3b, v123
	v_mul_f32_e32 v124, 0x3fb8aa3b, v124
	v_mul_f32_e32 v125, 0x3fb8aa3b, v125
	v_mul_f32_e32 v127, 0x3fb8aa3b, v127
	v_mul_f32_e32 v128, 0x3fb8aa3b, v128
	v_mul_f32_e32 v129, 0x3fb8aa3b, v129
	v_exp_f32_e32 v126, v126
	v_exp_f32_e32 v122, v122
	v_exp_f32_e32 v123, v123
	v_exp_f32_e32 v124, v124
	v_exp_f32_e32 v125, v125
	v_exp_f32_e32 v127, v127
	v_exp_f32_e32 v128, v128
	v_exp_f32_e32 v129, v129
	v_pk_mul_f32 v[30:31], v[30:31], v[64:65] op_sel_hi:[1,0]
	v_pk_mul_f32 v[28:29], v[28:29], v[64:65] op_sel_hi:[1,0]
	v_pk_mul_f32 v[26:27], v[26:27], v[64:65] op_sel_hi:[1,0]
	v_pk_mul_f32 v[24:25], v[24:25], v[64:65] op_sel_hi:[1,0]
	v_pk_mul_f32 v[22:23], v[22:23], v[64:65] op_sel_hi:[1,0]
	v_pk_mul_f32 v[20:21], v[20:21], v[64:65] op_sel_hi:[1,0]
	v_pk_mul_f32 v[18:19], v[18:19], v[64:65] op_sel_hi:[1,0]
	v_pk_mul_f32 v[16:17], v[16:17], v[64:65] op_sel_hi:[1,0]
	v_cndmask_b32_e64 v126, 0, v126, s[70:71]
	v_cndmask_b32_e64 v122, 0, v122, s[72:73]
	s_waitcnt vmcnt(1)
	v_permlane32_swap_b32_e32 v40, v42
	v_permlane32_swap_b32_e32 v41, v43
	s_nop 1
	v_mfma_f32_32x32x16_bf16 v[16:31], v[40:43], v[118:121], v[16:31]
	v_add_f32_e32 v40, 0, v132
	v_cndmask_b32_e64 v123, 0, v123, s[74:75]
	v_cndmask_b32_e64 v124, 0, v124, s[76:77]
	v_cndmask_b32_e64 v125, 0, v125, s[78:79]
	v_cndmask_b32_e64 v127, 0, v127, s[80:81]
	v_cndmask_b32_e64 v128, 0, v128, s[82:83]
	v_cndmask_b32_e64 v129, 0, v129, s[84:85]
	v_add_f32_e32 v40, v133, v40
	v_cvt_pk_bf16_f32 v32, v126, v122
	v_cvt_pk_bf16_f32 v33, v123, v124
	v_cvt_pk_bf16_f32 v34, v125, v127
	v_cvt_pk_bf16_f32 v35, v128, v129
	v_add_f32_e32 v40, v134, v40
	s_movk_i32 s89, 0x2200
	v_permlane32_swap_b32_e32 v36, v38
	v_permlane32_swap_b32_e32 v37, v39
	s_nop 1
	v_mfma_f32_32x32x16_bf16 v[0:15], v[36:39], v[32:35], v[0:15]
	v_add_f32_e32 v36, v117, v40
	v_add_f32_e32 v36, v130, v36
	v_add_f32_e32 v36, v131, v36
	v_add_f32_e32 v36, v136, v36
	v_add_f32_e32 v36, v137, v36
	v_add_f32_e32 v36, v126, v36
	v_add_f32_e32 v36, v122, v36
	s_waitcnt vmcnt(0)
	v_permlane32_swap_b32_e32 v44, v46
	v_permlane32_swap_b32_e32 v45, v47
	s_nop 1
	v_mfma_f32_32x32x16_bf16 v[16:31], v[44:47], v[32:35], v[16:31]
	v_add_f32_e32 v32, v123, v36
	v_add_f32_e32 v32, v124, v32
	v_add_f32_e32 v32, v125, v32
	v_add_f32_e32 v32, v127, v32
	v_add_f32_e32 v32, v128, v32
	v_add_f32_e32 v117, v129, v32
	v_fmac_f32_e32 v117, v135, v64
	s_andn2_b64 exec, exec, s[0:1]
	s_cbranch_execnz .LBB0_248
	s_or_b64 exec, exec, s[0:1]
	v_readlane_b32 s68, v254, 25
	v_readlane_b32 s72, v254, 29
	v_readlane_b32 s73, v254, 30
	v_readlane_b32 s70, v254, 27
	v_readlane_b32 s71, v254, 28
	v_readlane_b32 s82, v254, 39
	v_readlane_b32 s83, v254, 40
	v_readlane_b32 s90, v254, 45
	v_readlane_b32 s86, v254, 47
	v_readlane_b32 s72, v254, 51
	v_readlane_b32 s16, v254, 59
	v_readlane_b32 s20, v254, 53
	v_readlane_b32 s22, v254, 55
	v_readlane_b32 s2, v254, 57
	s_mov_b64 s[70:71], s[82:83]
	v_readlane_b32 s91, v254, 46
	s_mov_b32 s88, s86
	s_mov_b32 s84, s72
	v_readlane_b32 s17, v254, 60
	v_readlane_b32 s21, v254, 54
	v_readlane_b32 s23, v254, 56
	v_readlane_b32 s3, v254, 58
	v_readlane_b32 s69, v254, 26
	v_readlane_b32 s74, v254, 31
	v_readlane_b32 s75, v254, 32
	v_readlane_b32 s76, v254, 33
	v_readlane_b32 s77, v254, 34
	v_readlane_b32 s78, v254, 35
	v_readlane_b32 s79, v254, 36
	v_readlane_b32 s80, v254, 37
	v_readlane_b32 s81, v254, 38
	v_readlane_b32 s87, v254, 48
	v_readlane_b32 s73, v254, 52
	s_branch .LBB0_243

.LBB0_831:
	s_or_b64 exec, exec, s[0:1]
	v_lshrrev_b32_e32 v0, 3, v69
	v_and_b32_e32 v1, 4, v69
	v_and_or_b32 v0, v0, 56, v1
	v_lshrrev_b32_e32 v0, 1, v0
	v_or_b32_e32 v87, v0, v106
	v_lshlrev_b32_e32 v1, 4, v69
	v_sub_u32_e64 v2, v0, 4 clamp
	v_sub_u32_e64 v0, v0, 3 clamp
	v_and_b32_e32 v36, 48, v1
	v_ashrrev_i32_e32 v35, 9, v69
	v_min_u32_e32 v91, 24, v2
	v_min_u32_e32 v0, 24, v0
	v_or_b32_e32 v32, v36, v107
	v_lshlrev_b32_e32 v1, 6, v87
	v_lshlrev_b32_e32 v34, 11, v35
	v_sub_u32_e32 v0, v0, v91
	v_or3_b32 v94, v1, v34, v32
	v_lshlrev_b32_e32 v1, 6, v33
	v_add_u32_e32 v110, 8, v0
	v_mov_b32_e32 v15, 0
	v_ashrrev_i32_e32 v95, 31, v94
	v_cmp_lt_i32_e32 vcc, 0, v110
	v_lshlrev_b32_e32 v96, 1, v1
	v_mov_b32_e32 v14, v15
	v_mov_b32_e32 v13, v15
	v_mov_b32_e32 v12, v15
	v_mov_b32_e32 v11, v15
	v_mov_b32_e32 v10, v15
	v_mov_b32_e32 v9, v15
	v_mov_b32_e32 v8, v15
	v_mov_b32_e32 v7, v15
	v_mov_b32_e32 v6, v15
	v_mov_b32_e32 v5, v15
	v_mov_b32_e32 v4, v15
	v_mov_b32_e32 v3, v15
	v_mov_b32_e32 v2, v15
	v_mov_b32_e32 v1, v15
	v_mov_b32_e32 v0, v15
	v_mov_b32_e32 v31, v15
	v_mov_b32_e32 v30, v15
	v_mov_b32_e32 v29, v15
	v_mov_b32_e32 v28, v15
	v_mov_b32_e32 v27, v15
	v_mov_b32_e32 v26, v15
	v_mov_b32_e32 v25, v15
	v_mov_b32_e32 v24, v15
	v_mov_b32_e32 v23, v15
	v_mov_b32_e32 v22, v15
	v_mov_b32_e32 v21, v15
	v_mov_b32_e32 v20, v15
	v_mov_b32_e32 v19, v15
	v_mov_b32_e32 v18, v15
	v_mov_b32_e32 v17, v15
	v_mov_b32_e32 v16, v15
	v_mov_b32_e32 v130, v15
	s_waitcnt lgkmcnt(0)
	s_and_saveexec_b64 s[2:3], vcc
	s_cbranch_execz .LBB0_828
	v_writelane_b32 v254, s2, 57
	v_max_i32_e32 v0, 4, v87
	v_add_u32_e32 v3, -4, v0
	v_writelane_b32 v254, s3, 58
	v_writelane_b32 v254, s16, 59
	v_mov_b32_e32 v97, v65
	v_mov_b32_e32 v89, v65
	v_writelane_b32 v254, s17, 60
	v_sub_u32_e64 v2, v36, 8 clamp
	v_readlane_b32 s0, v254, 55
	v_readlane_b32 s1, v254, 56
	v_min_u32_e32 v111, 24, v3
	v_mov_b32_e32 v130, 0
	v_mov_b64_e32 v[0:1], s[0:1]
	v_mad_i64_i32 v[0:1], s[0:1], v94, s85, v[0:1]
	v_lshl_add_u64 v[0:1], v[0:1], 0, v[96:97]
	v_lshl_add_u64 v[0:1], v[0:1], 0, v[88:89]
	global_load_dwordx4 v[48:51], v[0:1], off
	global_load_dwordx4 v[52:55], v[0:1], off offset:32
	global_load_dwordx4 v[56:59], v[0:1], off offset:64
	global_load_dwordx4 v[60:63], v[0:1], off offset:96
	v_min_u32_e32 v89, 32, v2
	v_or_b32_e32 v4, v89, v68
	v_max_i32_e32 v2, 8, v32
	v_sub_u32_e32 v5, v4, v32
	v_add_u32_e32 v161, 15, v5
	v_add_u32_e32 v2, -8, v2
	v_max_i32_e32 v5, -15, v5
	v_min_u32_e32 v2, 48, v2
	v_add_u32_e32 v5, 15, v5
	v_add_u32_e32 v3, 16, v2
	v_min_u32_e32 v114, 30, v5
	v_or_b32_e32 v5, 1, v4
	v_cmp_ge_u32_e64 s[8:9], v5, v2
	v_cmp_lt_u32_e64 s[10:11], v5, v3
	v_sub_u32_e32 v5, v5, v32
	v_max_i32_e32 v5, -15, v5
	v_add_u32_e32 v5, 15, v5
	v_min_u32_e32 v115, 30, v5
	v_or_b32_e32 v5, 2, v4
	v_cmp_ge_u32_e64 s[12:13], v5, v2
	v_cmp_lt_u32_e64 s[14:15], v5, v3
	v_sub_u32_e32 v5, v5, v32
	v_max_i32_e32 v5, -15, v5
	v_add_u32_e32 v5, 15, v5
	v_min_u32_e32 v116, 30, v5
	v_or_b32_e32 v5, 3, v4
	v_cmp_ge_u32_e64 s[16:17], v5, v2
	v_cmp_lt_u32_e64 s[18:19], v5, v3
	v_sub_u32_e32 v5, v5, v32
	v_max_i32_e32 v5, -15, v5
	v_add_u32_e32 v5, 15, v5
	v_min_u32_e32 v117, 30, v5
	v_add_u32_e32 v5, 8, v4
	v_cmp_ge_u32_e64 s[20:21], v5, v2
	v_cmp_lt_u32_e64 s[22:23], v5, v3
	v_sub_u32_e32 v5, v5, v32
	v_max_i32_e32 v5, -15, v5
	v_add_u32_e32 v5, 15, v5
	v_min_u32_e32 v118, 30, v5
	v_add_u32_e32 v5, 9, v4
	v_cmp_ge_u32_e64 s[24:25], v5, v2
	v_cmp_lt_u32_e64 s[26:27], v5, v3
	v_sub_u32_e32 v5, v5, v32
	v_max_i32_e32 v5, -15, v5
	v_add_u32_e32 v5, 15, v5
	v_min_u32_e32 v119, 30, v5
	v_add_u32_e32 v5, 10, v4
	v_cmp_ge_u32_e64 s[28:29], v5, v2
	v_cmp_lt_u32_e64 s[30:31], v5, v3
	v_sub_u32_e32 v5, v5, v32
	v_max_i32_e32 v5, -15, v5
	v_add_u32_e32 v5, 15, v5
	v_min_u32_e32 v120, 30, v5
	v_add_u32_e32 v5, 11, v4
	v_cmp_ge_u32_e64 s[34:35], v5, v2
	v_cmp_lt_u32_e64 s[36:37], v5, v3
	v_sub_u32_e32 v5, v5, v32
	v_max_i32_e32 v5, -15, v5
	v_add_u32_e32 v5, 15, v5
	v_min_u32_e32 v121, 30, v5
	v_add_u32_e32 v5, 16, v4
	v_cmp_ge_u32_e64 s[38:39], v5, v2
	v_sub_u32_e32 v5, v5, v32
	v_max_i32_e32 v5, -15, v5
	v_add_u32_e32 v5, 15, v5
	v_min_u32_e32 v122, 30, v5
	v_add_u32_e32 v5, 17, v4
	v_cmp_ge_u32_e64 s[42:43], v5, v2
	v_cmp_lt_u32_e64 s[44:45], v5, v3
	v_sub_u32_e32 v5, v5, v32
	v_max_i32_e32 v5, -15, v5
	v_add_u32_e32 v5, 15, v5
	v_min_u32_e32 v123, 30, v5
	v_add_u32_e32 v5, 18, v4
	v_cmp_ge_u32_e64 s[46:47], v5, v2
	v_cmp_lt_u32_e64 s[48:49], v5, v3
	v_sub_u32_e32 v5, v5, v32
	v_max_i32_e32 v5, -15, v5
	v_add_u32_e32 v5, 15, v5
	v_min_u32_e32 v124, 30, v5
	v_add_u32_e32 v5, 19, v4
	v_cmp_ge_u32_e64 s[50:51], v5, v2
	v_cmp_lt_u32_e64 s[52:53], v5, v3
	v_sub_u32_e32 v5, v5, v32
	v_max_i32_e32 v5, -15, v5
	v_add_u32_e32 v5, 15, v5
	v_min_u32_e32 v125, 30, v5
	v_add_u32_e32 v5, 24, v4
	v_cmp_ge_u32_e64 s[54:55], v5, v2
	v_cmp_lt_u32_e64 s[56:57], v5, v3
	v_sub_u32_e32 v5, v5, v32
	v_max_i32_e32 v5, -15, v5
	v_add_u32_e32 v5, 15, v5
	v_mad_i32_i24 v0, v35, 10, v33
	v_min_u32_e32 v126, 30, v5
	v_add_u32_e32 v5, 25, v4
	v_ashrrev_i32_e32 v1, 31, v0
	v_cmp_ge_u32_e64 s[58:59], v5, v2
	v_cmp_lt_u32_e64 s[60:61], v5, v3
	v_sub_u32_e32 v5, v5, v32
	v_lshlrev_b64 v[0:1], 18, v[0:1]
	v_max_i32_e32 v5, -15, v5
	v_lshl_add_u64 v[0:1], v[66:67], 0, v[0:1]
	s_mov_b64 s[0:1], 0x20000
	v_add_u32_e32 v5, 15, v5
	v_lshl_add_u64 v[98:99], v[0:1], 0, s[0:1]
	v_cmp_ge_u32_e64 s[0:1], v4, v2
	v_cmp_lt_u32_e64 s[6:7], v4, v3
	v_cmp_lt_u32_e64 s[40:41], v4, v2
	v_min_u32_e32 v127, 30, v5
	v_add_u32_e32 v5, 26, v4
	v_add_u32_e32 v4, 27, v4
	v_cmp_ge_u32_e64 s[62:63], v5, v2
	v_cmp_lt_u32_e64 s[64:65], v5, v3
	v_sub_u32_e32 v5, v5, v32
	v_cmp_ge_u32_e64 s[66:67], v4, v2
	v_sub_u32_e32 v2, v4, v32
	v_max_i32_e32 v5, -15, v5
	v_max_i32_e32 v2, -15, v2
	v_writelane_b32 v254, s0, 61
	v_add_u32_e32 v5, 15, v5
	v_add_u32_e32 v2, 15, v2
	v_or_b32_e32 v112, v34, v104
	v_add_u32_e32 v113, 8, v111
	v_writelane_b32 v254, s1, 62
	v_min_u32_e32 v128, 30, v5
	v_cmp_lt_u32_e64 s[68:69], v4, v3
	v_min_u32_e32 v129, 30, v2
	v_lshl_add_u64 v[100:101], v[70:71], 0, v[96:97]
	v_lshl_add_u64 v[102:103], v[0:1], 0, v[92:93]
	s_mov_b32 s33, 0
	v_mov_b32_e32 v97, 0xf149f2ca
	s_mov_b64 s[0:1], 0
	v_mov_b32_e32 v0, 0
	v_mov_b32_e32 v1, v130
	v_mov_b32_e32 v2, v130
	v_mov_b32_e32 v3, v130
	v_mov_b32_e32 v4, v130
	v_mov_b32_e32 v5, v130
	v_mov_b32_e32 v6, v130
	v_mov_b32_e32 v7, v130
	v_mov_b32_e32 v8, v130
	v_mov_b32_e32 v9, v130
	v_mov_b32_e32 v10, v130
	v_mov_b32_e32 v11, v130
	v_mov_b32_e32 v12, v130
	v_mov_b32_e32 v13, v130
	v_mov_b32_e32 v14, v130
	v_mov_b32_e32 v15, v130
	v_mov_b32_e32 v16, 0
	v_mov_b32_e32 v17, v130
	v_mov_b32_e32 v18, v130
	v_mov_b32_e32 v19, v130
	v_mov_b32_e32 v20, v130
	v_mov_b32_e32 v21, v130
	v_mov_b32_e32 v22, v130
	v_mov_b32_e32 v23, v130
	v_mov_b32_e32 v24, v130
	v_mov_b32_e32 v25, v130
	v_mov_b32_e32 v26, v130
	v_mov_b32_e32 v27, v130
	v_mov_b32_e32 v28, v130
	v_mov_b32_e32 v29, v130
	v_mov_b32_e32 v30, v130
	v_mov_b32_e32 v31, v130
	v_lshrrev_b32_e32 v164, 5, v179
	v_lshlrev_b32_e32 v164, 3, v164
	v_mov_b32_e32 v165, 0
.LBB0_833:
	v_add_u32_e32 v32, s33, v91
	v_lshl_or_b32 v64, v32, 6, v89
	v_sub_u32_e32 v33, v32, v87
	v_cmp_ge_u32_e32 vcc, v32, v111
	v_cmp_lt_u32_e64 s[2:3], v32, v113
	v_add_u32_e32 v32, v112, v64
	v_max_i32_e32 v33, -7, v33
	s_and_b64 s[86:87], vcc, s[2:3]
	v_mad_i64_i32 v[36:37], s[2:3], v32, s85, v[100:101]
	v_add_u32_e32 v38, 7, v33
	global_load_dwordx4 v[32:35], v[36:37], off offset:1024
	global_load_dwordx4 v[132:135], v[36:37], off offset:1056
	global_load_dwordx4 v[136:139], v[36:37], off offset:1088
	global_load_dwordx4 v[140:143], v[36:37], off offset:1120
	v_min_u32_e32 v36, 14, v38
	s_movk_i32 vcc_lo, 0x7c
	v_mad_u32_u24 v131, v36, vcc_lo, v105
	v_lshl_add_u32 v160, v161, 2, v131
	ds_read_b32 v144, v160
	ds_read_b32 v145, v160 offset:4
	v_readlane_b32 s2, v254, 61
	v_readlane_b32 s3, v254, 62
	s_and_b64 s[2:3], s[86:87], s[2:3]
	s_and_b64 s[4:5], s[86:87], s[8:9]
	s_and_b64 s[96:97], s[86:87], s[12:13]
	s_and_b64 s[94:95], s[86:87], s[16:17]
	s_and_b64 s[4:5], s[4:5], s[10:11]
	s_and_b64 s[2:3], s[2:3], s[6:7]
	s_and_b64 s[92:93], s[86:87], s[20:21]
	s_and_b64 s[90:91], s[86:87], s[24:25]
	s_and_b64 s[96:97], s[96:97], s[14:15]
	s_and_b64 s[94:95], s[94:95], s[18:19]
	s_and_b64 s[88:89], s[86:87], s[28:29]
	s_and_b64 s[70:71], s[86:87], s[34:35]
	s_and_b64 s[92:93], s[92:93], s[22:23]
	s_and_b64 s[90:91], s[90:91], s[26:27]
	s_and_b64 s[72:73], s[86:87], s[38:39]
	s_and_b64 s[74:75], s[86:87], s[42:43]
	s_and_b64 s[88:89], s[88:89], s[30:31]
	s_and_b64 s[70:71], s[70:71], s[36:37]
	s_and_b64 s[76:77], s[86:87], s[46:47]
	s_and_b64 s[78:79], s[86:87], s[50:51]
	s_and_b64 s[72:73], s[72:73], s[40:41]
	s_and_b64 s[74:75], s[74:75], s[44:45]
	s_and_b64 s[80:81], s[86:87], s[54:55]
	s_and_b64 s[82:83], s[86:87], s[58:59]
	s_and_b64 s[76:77], s[76:77], s[48:49]
	s_and_b64 s[78:79], s[78:79], s[52:53]
	s_and_b64 s[84:85], s[86:87], s[62:63]
	s_and_b64 s[86:87], s[86:87], s[66:67]
	s_and_b64 s[80:81], s[80:81], s[56:57]
	s_and_b64 s[82:83], s[82:83], s[60:61]
	s_and_b64 s[84:85], s[84:85], s[64:65]
	s_and_b64 s[86:87], s[86:87], s[68:69]
	s_add_i32 s33, s33, 1
	v_cmp_ge_i32_e32 vcc, s33, v110
	s_or_b64 s[0:1], vcc, s[0:1]
	s_waitcnt vmcnt(3)
	v_mfma_f32_32x32x16_bf16 v[32:47], v[32:35], v[48:51], 0
	s_waitcnt vmcnt(2)
	v_mfma_f32_32x32x16_bf16 v[32:47], v[132:135], v[52:55], v[32:47]
	ds_read_b32 v132, v160 offset:8
	ds_read_b32 v133, v160 offset:12
	ds_read_b32 v134, v160 offset:32
	ds_read_b32 v135, v160 offset:36
	ds_read_b32 v146, v160 offset:40
	ds_read_b32 v147, v160 offset:44
	ds_read_b32 v148, v160 offset:64
	s_waitcnt vmcnt(1)
	v_mfma_f32_32x32x16_bf16 v[32:47], v[136:139], v[56:59], v[32:47]
	ds_read_b32 v136, v160 offset:68
	ds_read_b32 v137, v160 offset:72
	ds_read_b32 v138, v160 offset:76
	ds_read_b32 v139, v160 offset:96
	ds_read_b32 v149, v160 offset:100
	ds_read_b32 v150, v160 offset:104
	ds_read_b32 v131, v160 offset:108
	s_waitcnt vmcnt(0)
	v_mfma_f32_32x32x16_bf16 v[32:47], v[140:143], v[60:63], v[32:47]
	s_waitcnt lgkmcnt(14)
	s_nop 10
	v_add_f32_e32 v32, v32, v144
	v_add_f32_e32 v33, v33, v145
	s_waitcnt lgkmcnt(13)
	v_add_f32_e32 v34, v34, v132
	s_waitcnt lgkmcnt(12)
	v_add_f32_e32 v132, v35, v133
	v_max_f32_e32 v35, 0xf149f2ca, v32
	s_waitcnt lgkmcnt(11)
	v_add_f32_e32 v133, v36, v134
	v_cndmask_b32_e64 v36, v109, v33, s[4:5]
	v_cndmask_b32_e64 v35, v109, v35, s[2:3]
	s_waitcnt lgkmcnt(10)
	v_add_f32_e32 v134, v37, v135
	s_waitcnt lgkmcnt(9)
	v_add_f32_e32 v135, v38, v146
	v_cndmask_b32_e64 v37, v109, v34, s[96:97]
	v_cndmask_b32_e64 v38, v109, v132, s[94:95]
	v_max_f32_e32 v35, v35, v36
	s_waitcnt lgkmcnt(8)
	v_add_f32_e32 v140, v39, v147
	s_waitcnt lgkmcnt(7)
	v_add_f32_e32 v141, v40, v148
	v_cndmask_b32_e64 v39, v109, v133, s[92:93]
	v_cndmask_b32_e64 v40, v109, v134, s[90:91]
	v_max3_f32 v35, v35, v37, v38
	s_waitcnt lgkmcnt(6)
	v_add_f32_e32 v136, v41, v136
	s_waitcnt lgkmcnt(5)
	v_add_f32_e32 v137, v42, v137
	v_cndmask_b32_e64 v41, v109, v135, s[88:89]
	v_cndmask_b32_e64 v42, v109, v140, s[70:71]
	v_max3_f32 v35, v35, v39, v40
	s_waitcnt lgkmcnt(4)
	v_add_f32_e32 v138, v43, v138
	s_waitcnt lgkmcnt(3)
	v_add_f32_e32 v139, v44, v139
	v_cndmask_b32_e64 v43, v109, v141, s[72:73]
	v_cndmask_b32_e64 v44, v109, v136, s[74:75]
	v_max3_f32 v35, v35, v41, v42
	s_waitcnt lgkmcnt(2)
	v_add_f32_e32 v142, v45, v149
	s_waitcnt lgkmcnt(1)
	v_add_f32_e32 v143, v46, v150
	v_cndmask_b32_e64 v45, v109, v137, s[76:77]
	v_cndmask_b32_e64 v46, v109, v138, s[78:79]
	v_max3_f32 v35, v35, v43, v44
	s_waitcnt lgkmcnt(0)
	v_add_f32_e32 v131, v47, v131
	v_cndmask_b32_e64 v47, v109, v139, s[80:81]
	v_cndmask_b32_e64 v144, v109, v142, s[82:83]
	v_max3_f32 v35, v35, v45, v46
	v_cndmask_b32_e64 v145, v109, v143, s[84:85]
	v_cndmask_b32_e64 v146, v109, v131, s[86:87]
	v_max3_f32 v35, v35, v47, v144
	v_max3_f32 v35, v35, v145, v146
	v_mov_b32_e32 v36, v35
	s_nop 1
	v_permlane32_swap_b32_e32 v35, v36
	v_max3_f32 v144, v97, v35, v36
	v_sub_f32_e32 v32, v32, v144
	v_mul_f32_e32 v32, 0x3fb8aa3b, v32
	v_exp_f32_e32 v32, v32
	v_mov_b32_e32 v148, v130
	v_sub_f32_e32 v130, v132, v144
	v_sub_f32_e32 v132, v133, v144
	v_cndmask_b32_e64 v145, 0, v32, s[2:3]
	v_sub_f32_e32 v32, v33, v144
	v_mul_f32_e32 v32, 0x3fb8aa3b, v32
	v_exp_f32_e32 v32, v32
	v_sub_f32_e32 v133, v134, v144
	v_sub_f32_e32 v134, v135, v144
	v_sub_f32_e32 v135, v140, v144
	v_cndmask_b32_e64 v146, 0, v32, s[4:5]
	v_sub_f32_e32 v32, v34, v144
	v_mul_f32_e32 v32, 0x3fb8aa3b, v32
	v_exp_f32_e32 v32, v32
	v_sub_f32_e32 v131, v131, v144
	v_mul_f32_e32 v130, 0x3fb8aa3b, v130
	v_mul_f32_e32 v132, 0x3fb8aa3b, v132
	v_cndmask_b32_e64 v147, 0, v32, s[96:97]
	v_lshlrev_b64 v[32:33], 1, v[64:65]
	v_lshl_add_u64 v[38:39], v[102:103], 0, v[32:33]
	v_lshl_add_u64 v[38:39], v[38:39], 0, v[164:165]
	v_lshl_add_u64 v[36:37], v[98:99], 0, v[32:33]
	global_load_dwordx4 v[32:35], v[38:39], off
	v_lshl_add_u64 v[46:47], v[36:37], 0, v[92:93]
	v_lshl_add_u64 v[46:47], v[46:47], 0, v[164:165]
	global_load_dwordx4 v[36:39], v[38:39], off offset:32
	s_nop 0
	s_nop 0
	global_load_dwordx4 v[40:43], v[46:47], off
	global_load_dwordx4 v[44:47], v[46:47], off offset:32
	s_nop 0
	v_sub_f32_e32 v64, v97, v144
	v_mul_f32_e32 v133, 0x3fb8aa3b, v133
	v_mul_f32_e32 v134, 0x3fb8aa3b, v134
	v_mul_f32_e32 v135, 0x3fb8aa3b, v135
	v_mul_f32_e32 v64, 0x3fb8aa3b, v64
	v_mul_f32_e32 v131, 0x3fb8aa3b, v131
	v_exp_f32_e32 v130, v130
	v_exp_f32_e32 v132, v132
	v_exp_f32_e32 v133, v133
	v_exp_f32_e32 v134, v134
	v_exp_f32_e32 v135, v135
	v_exp_f32_e32 v131, v131
	v_exp_f32_e32 v64, v64
	v_sub_f32_e32 v140, v141, v144
	v_sub_f32_e32 v136, v136, v144
	v_sub_f32_e32 v137, v137, v144
	v_sub_f32_e32 v138, v138, v144
	v_sub_f32_e32 v139, v139, v144
	v_sub_f32_e32 v141, v142, v144
	v_sub_f32_e32 v142, v143, v144
	v_mov_b32_e32 v97, v144
	v_cndmask_b32_e64 v143, 0, v130, s[94:95]
	v_cndmask_b32_e64 v144, 0, v132, s[92:93]
	v_cndmask_b32_e64 v149, 0, v133, s[90:91]
	v_cndmask_b32_e64 v134, 0, v134, s[88:89]
	v_cndmask_b32_e64 v135, 0, v135, s[70:71]
	v_cndmask_b32_e64 v150, 0, v131, s[86:87]
	v_pk_mul_f32 v[14:15], v[14:15], v[64:65] op_sel_hi:[1,0]
	v_pk_mul_f32 v[12:13], v[12:13], v[64:65] op_sel_hi:[1,0]
	v_pk_mul_f32 v[10:11], v[10:11], v[64:65] op_sel_hi:[1,0]
	v_pk_mul_f32 v[8:9], v[8:9], v[64:65] op_sel_hi:[1,0]
	v_pk_mul_f32 v[6:7], v[6:7], v[64:65] op_sel_hi:[1,0]
	v_pk_mul_f32 v[4:5], v[4:5], v[64:65] op_sel_hi:[1,0]
	v_pk_mul_f32 v[2:3], v[2:3], v[64:65] op_sel_hi:[1,0]
	v_pk_mul_f32 v[0:1], v[0:1], v[64:65] op_sel_hi:[1,0]
	v_cvt_pk_bf16_f32 v130, v145, v146
	v_cvt_pk_bf16_f32 v131, v147, v143
	v_cvt_pk_bf16_f32 v132, v144, v149
	v_cvt_pk_bf16_f32 v133, v134, v135
	v_mul_f32_e32 v140, 0x3fb8aa3b, v140
	v_mul_f32_e32 v136, 0x3fb8aa3b, v136
	s_waitcnt vmcnt(3)
	v_permlane32_swap_b32_e32 v32, v34
	v_permlane32_swap_b32_e32 v33, v35
	s_nop 1
	v_mfma_f32_32x32x16_bf16 v[0:15], v[32:35], v[130:133], v[0:15]
	v_mul_f32_e32 v137, 0x3fb8aa3b, v137
	v_mul_f32_e32 v138, 0x3fb8aa3b, v138
	v_mul_f32_e32 v139, 0x3fb8aa3b, v139
	v_mul_f32_e32 v141, 0x3fb8aa3b, v141
	v_mul_f32_e32 v142, 0x3fb8aa3b, v142
	v_exp_f32_e32 v140, v140
	v_exp_f32_e32 v136, v136
	v_exp_f32_e32 v137, v137
	v_exp_f32_e32 v138, v138
	v_exp_f32_e32 v139, v139
	v_exp_f32_e32 v141, v141
	v_exp_f32_e32 v142, v142
	v_pk_mul_f32 v[30:31], v[30:31], v[64:65] op_sel_hi:[1,0]
	v_pk_mul_f32 v[28:29], v[28:29], v[64:65] op_sel_hi:[1,0]
	v_pk_mul_f32 v[26:27], v[26:27], v[64:65] op_sel_hi:[1,0]
	v_pk_mul_f32 v[24:25], v[24:25], v[64:65] op_sel_hi:[1,0]
	v_pk_mul_f32 v[22:23], v[22:23], v[64:65] op_sel_hi:[1,0]
	v_pk_mul_f32 v[20:21], v[20:21], v[64:65] op_sel_hi:[1,0]
	v_pk_mul_f32 v[18:19], v[18:19], v[64:65] op_sel_hi:[1,0]
	v_pk_mul_f32 v[16:17], v[16:17], v[64:65] op_sel_hi:[1,0]
	v_cndmask_b32_e64 v140, 0, v140, s[72:73]
	v_cndmask_b32_e64 v136, 0, v136, s[74:75]
	s_waitcnt vmcnt(1)
	v_permlane32_swap_b32_e32 v40, v42
	v_permlane32_swap_b32_e32 v41, v43
	s_nop 1
	v_mfma_f32_32x32x16_bf16 v[16:31], v[40:43], v[130:133], v[16:31]
	v_add_f32_e32 v40, 0, v145
	v_cndmask_b32_e64 v137, 0, v137, s[76:77]
	v_cndmask_b32_e64 v138, 0, v138, s[78:79]
	v_cndmask_b32_e64 v139, 0, v139, s[80:81]
	v_cndmask_b32_e64 v141, 0, v141, s[82:83]
	v_cndmask_b32_e64 v142, 0, v142, s[84:85]
	v_add_f32_e32 v40, v146, v40
	v_cvt_pk_bf16_f32 v32, v140, v136
	v_cvt_pk_bf16_f32 v33, v137, v138
	v_cvt_pk_bf16_f32 v34, v139, v141
	v_cvt_pk_bf16_f32 v35, v142, v150
	v_add_f32_e32 v40, v147, v40
	s_movk_i32 s85, 0x2200
	v_permlane32_swap_b32_e32 v36, v38
	v_permlane32_swap_b32_e32 v37, v39
	s_nop 1
	v_mfma_f32_32x32x16_bf16 v[0:15], v[36:39], v[32:35], v[0:15]
	v_add_f32_e32 v36, v143, v40
	v_add_f32_e32 v36, v144, v36
	v_add_f32_e32 v36, v149, v36
	v_add_f32_e32 v36, v134, v36
	v_add_f32_e32 v36, v135, v36
	v_add_f32_e32 v36, v140, v36
	v_add_f32_e32 v36, v136, v36
	s_waitcnt vmcnt(0)
	v_permlane32_swap_b32_e32 v44, v46
	v_permlane32_swap_b32_e32 v45, v47
	s_nop 1
	v_mfma_f32_32x32x16_bf16 v[16:31], v[44:47], v[32:35], v[16:31]
	v_add_f32_e32 v32, v137, v36
	v_add_f32_e32 v32, v138, v32
	v_add_f32_e32 v32, v139, v32
	v_add_f32_e32 v32, v141, v32
	v_add_f32_e32 v32, v142, v32
	v_add_f32_e32 v130, v150, v32
	v_fmac_f32_e32 v130, v148, v64
	s_andn2_b64 exec, exec, s[0:1]
	s_cbranch_execnz .LBB0_833
	s_or_b64 exec, exec, s[0:1]
	v_readlane_b32 s68, v254, 25
	v_readlane_b32 s72, v254, 29
	v_readlane_b32 s73, v254, 30
	v_readlane_b32 s88, v254, 47
	v_readlane_b32 s70, v254, 27
	v_readlane_b32 s71, v254, 28
	v_readlane_b32 s82, v254, 39
	v_readlane_b32 s83, v254, 40
	v_readlane_b32 s90, v254, 45
	v_readlane_b32 s89, v254, 48
	v_readlane_b32 s72, v254, 51
	v_readlane_b32 s92, v254, 53
	v_readlane_b32 s16, v254, 59
	v_readlane_b32 s18, v254, 41
	v_readlane_b32 s20, v254, 43
	v_readlane_b32 s2, v254, 57
	s_mov_b64 s[70:71], s[82:83]
	v_readlane_b32 s91, v254, 46
	s_mov_b32 s84, s72
	v_readlane_b32 s89, v254, 49
	v_readlane_b32 s93, v254, 54
	v_readlane_b32 s17, v254, 60
	v_readlane_b32 s19, v254, 42
	v_readlane_b32 s21, v254, 44
	v_readlane_b32 s3, v254, 58
	v_readlane_b32 s69, v254, 26
	v_readlane_b32 s74, v254, 31
	v_readlane_b32 s75, v254, 32
	v_readlane_b32 s76, v254, 33
	v_readlane_b32 s77, v254, 34
	v_readlane_b32 s78, v254, 35
	v_readlane_b32 s79, v254, 36
	v_readlane_b32 s80, v254, 37
	v_readlane_b32 s81, v254, 38
	v_readlane_b32 s73, v254, 52
	s_branch .LBB0_828
